# attention: real static priority split by scalar branch, younger half (waves 4-7) s_setprio 1, older half 0 (baseline code executed both setprio on every wave)
# speedup vs baseline: 1.0114x; 1.0114x over previous
.LBB0_96:
	s_lshl_b32 s23, s38, 11
	s_and_b32 s22, s39, s37
	s_addk_i32 s23, 0x2000
	s_lshl_b32 s24, s38, 8
	s_and_b64 s[12:13], s[12:13], exec
	s_cselect_b32 s24, s23, s24
	s_lshl_b32 s25, s22, 7
	s_waitcnt lgkmcnt(0)
	s_add_u32 s12, s4, s29
	s_addc_u32 s13, s5, 0
	s_add_u32 s22, s12, 0x629c000
	s_addc_u32 s23, s13, 0
	global_load_dword v113, v192, s[12:13]
	global_load_dword v112, v133, s[22:23] offset:8
	s_mov_b64 s[12:13], s[0:1]
	s_load_dwordx2 s[12:13], s[12:13], 0x68
	v_lshlrev_b32_e32 v0, 2, v40
	v_and_b32_e32 v0, 60, v0
	v_ashrrev_i32_e32 v13, 4, v40
	v_lshl_or_b32 v12, s35, 6, v0
	v_add_u32_e32 v29, s25, v13
	v_lshlrev_b32_e32 v0, 2, v12
	v_lshlrev_b32_e32 v132, 1, v12
	v_add_u32_e32 v18, s24, v29
	v_ashrrev_i32_e32 v19, 31, v18
	s_waitcnt lgkmcnt(0)
	s_add_u32 s12, s12, s6
	s_addc_u32 s13, s13, s7
	global_load_dwordx4 v[8:11], v0, s[12:13]
	global_load_dwordx4 v[4:7], v0, s[12:13] offset:1024
	s_nop 0
	global_load_dwordx4 v[0:3], v0, s[12:13] offset:2048
	v_lshl_add_u64 v[14:15], s[4:5], 0, v[132:133]
	v_lshlrev_b64 v[20:21], 9, v[18:19]
	s_mov_b64 s[12:13], 0xdea4400
	v_lshl_add_u64 v[16:17], v[14:15], 0, s[12:13]
	s_mov_b64 s[12:13], 0xe6a4400
	v_lshl_add_u64 v[22:23], v[14:15], 0, s[12:13]
	s_mov_b64 s[12:13], 0xd6a4400
	v_lshl_add_u64 v[24:25], v[14:15], 0, s[12:13]
	v_lshl_add_u64 v[16:17], v[16:17], 0, v[20:21]
	v_lshl_add_u64 v[22:23], v[22:23], 0, v[20:21]
	v_lshl_add_u64 v[24:25], v[24:25], 0, v[20:21]
	global_load_dwordx2 v[44:45], v[16:17], off offset:-512
	global_load_dwordx2 v[46:47], v[16:17], off
	global_load_dwordx2 v[48:49], v[16:17], off offset:512
	global_load_dwordx2 v[50:51], v[22:23], off offset:-512
	global_load_dwordx2 v[52:53], v[22:23], off
	global_load_dwordx2 v[54:55], v[22:23], off offset:512
	global_load_dwordx2 v[56:57], v[24:25], off
	v_lshl_add_u64 v[16:17], v[16:17], 0, s[76:77]
	v_lshl_add_u64 v[22:23], v[22:23], 0, s[76:77]
	v_lshl_add_u64 v[24:25], v[24:25], 0, s[76:77]
	global_load_dwordx2 v[58:59], v[16:17], off offset:-512
	global_load_dwordx2 v[60:61], v[16:17], off
	global_load_dwordx2 v[62:63], v[16:17], off offset:512
	global_load_dwordx2 v[64:65], v[22:23], off offset:-512
	global_load_dwordx2 v[66:67], v[22:23], off
	global_load_dwordx2 v[68:69], v[22:23], off offset:512
	global_load_dwordx2 v[70:71], v[24:25], off
	v_lshl_add_u64 v[16:17], v[16:17], 0, s[76:77]
	v_lshl_add_u64 v[22:23], v[22:23], 0, s[76:77]
	v_lshl_add_u64 v[24:25], v[24:25], 0, s[76:77]
	global_load_dwordx2 v[72:73], v[16:17], off offset:-512
	global_load_dwordx2 v[74:75], v[16:17], off
	global_load_dwordx2 v[76:77], v[16:17], off offset:512
	global_load_dwordx2 v[78:79], v[22:23], off offset:-512
	global_load_dwordx2 v[80:81], v[22:23], off
	global_load_dwordx2 v[82:83], v[22:23], off offset:512
	global_load_dwordx2 v[84:85], v[24:25], off
	v_lshl_add_u64 v[16:17], v[16:17], 0, s[76:77]
	v_lshl_add_u64 v[22:23], v[22:23], 0, s[76:77]
	v_lshl_add_u64 v[24:25], v[24:25], 0, s[76:77]
	global_load_dwordx2 v[86:87], v[16:17], off offset:-512
	global_load_dwordx2 v[88:89], v[16:17], off
	global_load_dwordx2 v[90:91], v[16:17], off offset:512
	global_load_dwordx2 v[92:93], v[22:23], off offset:-512
	global_load_dwordx2 v[94:95], v[22:23], off
	global_load_dwordx2 v[96:97], v[22:23], off offset:512
	global_load_dwordx2 v[98:99], v[24:25], off
	s_add_u32 s12, s4, 0xfea4400
	s_addc_u32 s13, s5, 0
	v_mov_b64_e32 v[26:27], s[12:13]
	v_mad_i64_i32 v[26:27], s[22:23], v18, s96, v[26:27]
	v_lshl_add_u64 v[26:27], v[26:27], 0, v[132:133]
	s_mov_b64 s[12:13], 0x14000
	v_add_u32_e32 v28, 0x60, v29
	s_waitcnt vmcnt(21)
	v_lshlrev_b32_e32 v100, 16, v44
	v_and_b32_e32 v101, 0xffff0000, v44
	v_lshlrev_b32_e32 v102, 16, v50
	v_and_b32_e32 v103, 0xffff0000, v50
	v_lshlrev_b32_e32 v104, 16, v45
	v_and_b32_e32 v105, 0xffff0000, v45
	v_lshlrev_b32_e32 v106, 16, v51
	v_and_b32_e32 v107, 0xffff0000, v51
	v_pk_mul_f32 v[30:31], v[100:101], v[102:103]
	v_pk_mul_f32 v[32:33], v[104:105], v[106:107]
	v_lshlrev_b32_e32 v100, 16, v46
	v_and_b32_e32 v101, 0xffff0000, v46
	v_lshlrev_b32_e32 v102, 16, v52
	v_and_b32_e32 v103, 0xffff0000, v52
	v_lshlrev_b32_e32 v104, 16, v47
	v_and_b32_e32 v105, 0xffff0000, v47
	v_lshlrev_b32_e32 v106, 16, v53
	v_and_b32_e32 v107, 0xffff0000, v53
	v_pk_mul_f32 v[34:35], v[100:101], v[102:103]
	v_pk_mul_f32 v[36:37], v[104:105], v[106:107]
	v_lshlrev_b32_e32 v100, 16, v48
	v_and_b32_e32 v101, 0xffff0000, v48
	v_lshlrev_b32_e32 v102, 16, v54
	v_and_b32_e32 v103, 0xffff0000, v54
	v_lshlrev_b32_e32 v104, 16, v49
	v_and_b32_e32 v105, 0xffff0000, v49
	v_lshlrev_b32_e32 v106, 16, v55
	v_and_b32_e32 v107, 0xffff0000, v55
	v_pk_mul_f32 v[108:109], v[100:101], v[102:103]
	v_pk_mul_f32 v[110:111], v[104:105], v[106:107]
	v_cmp_lt_i32_e32 vcc, 0, v29
	s_nop 1
	v_cndmask_b32_e32 v30, 0, v30, vcc
	v_cndmask_b32_e32 v31, 0, v31, vcc
	v_cndmask_b32_e32 v32, 0, v32, vcc
	v_cndmask_b32_e32 v33, 0, v33, vcc
	v_pk_mul_f32 v[32:33], v[10:11], v[32:33]
	v_pk_mul_f32 v[30:31], v[8:9], v[30:31]
	v_pk_fma_f32 v[32:33], v[6:7], v[36:37], v[32:33]
	v_pk_fma_f32 v[30:31], v[4:5], v[34:35], v[30:31]
	v_pk_fma_f32 v[30:31], v[0:1], v[108:109], v[30:31]
	v_pk_fma_f32 v[32:33], v[2:3], v[110:111], v[32:33]
	v_lshlrev_b32_e32 v100, 16, v56
	v_and_b32_e32 v101, 0xffff0000, v56
	v_lshlrev_b32_e32 v102, 16, v57
	v_and_b32_e32 v103, 0xffff0000, v57
	v_pk_mul_f32 v[32:33], v[32:33], v[102:103]
	v_pk_mul_f32 v[30:31], v[30:31], v[100:101]
	v_cvt_pk_bf16_f32 v30, v30, v31
	v_cvt_pk_bf16_f32 v31, v32, v33
	global_store_dwordx2 v[26:27], v[30:31], off offset:1024
	v_lshl_add_u64 v[26:27], v[26:27], 0, s[12:13]
	s_waitcnt vmcnt(14)
	v_lshlrev_b32_e32 v100, 16, v58
	v_and_b32_e32 v101, 0xffff0000, v58
	v_lshlrev_b32_e32 v102, 16, v64
	v_and_b32_e32 v103, 0xffff0000, v64
	v_lshlrev_b32_e32 v104, 16, v59
	v_and_b32_e32 v105, 0xffff0000, v59
	v_lshlrev_b32_e32 v106, 16, v65
	v_and_b32_e32 v107, 0xffff0000, v65
	v_pk_mul_f32 v[30:31], v[100:101], v[102:103]
	v_pk_mul_f32 v[32:33], v[104:105], v[106:107]
	v_lshlrev_b32_e32 v100, 16, v60
	v_and_b32_e32 v101, 0xffff0000, v60
	v_lshlrev_b32_e32 v102, 16, v66
	v_and_b32_e32 v103, 0xffff0000, v66
	v_lshlrev_b32_e32 v104, 16, v61
	v_and_b32_e32 v105, 0xffff0000, v61
	v_lshlrev_b32_e32 v106, 16, v67
	v_and_b32_e32 v107, 0xffff0000, v67
	v_pk_mul_f32 v[34:35], v[100:101], v[102:103]
	v_pk_mul_f32 v[36:37], v[104:105], v[106:107]
	v_lshlrev_b32_e32 v100, 16, v62
	v_and_b32_e32 v101, 0xffff0000, v62
	v_lshlrev_b32_e32 v102, 16, v68
	v_and_b32_e32 v103, 0xffff0000, v68
	v_lshlrev_b32_e32 v104, 16, v63
	v_and_b32_e32 v105, 0xffff0000, v63
	v_lshlrev_b32_e32 v106, 16, v69
	v_and_b32_e32 v107, 0xffff0000, v69
	v_pk_mul_f32 v[108:109], v[100:101], v[102:103]
	v_pk_mul_f32 v[110:111], v[104:105], v[106:107]
	v_pk_mul_f32 v[32:33], v[10:11], v[32:33]
	v_pk_mul_f32 v[30:31], v[8:9], v[30:31]
	v_pk_fma_f32 v[32:33], v[6:7], v[36:37], v[32:33]
	v_pk_fma_f32 v[30:31], v[4:5], v[34:35], v[30:31]
	v_pk_fma_f32 v[30:31], v[0:1], v[108:109], v[30:31]
	v_pk_fma_f32 v[32:33], v[2:3], v[110:111], v[32:33]
	v_lshlrev_b32_e32 v100, 16, v70
	v_and_b32_e32 v101, 0xffff0000, v70
	v_lshlrev_b32_e32 v102, 16, v71
	v_and_b32_e32 v103, 0xffff0000, v71
	v_pk_mul_f32 v[32:33], v[32:33], v[102:103]
	v_pk_mul_f32 v[30:31], v[30:31], v[100:101]
	v_cvt_pk_bf16_f32 v30, v30, v31
	v_cvt_pk_bf16_f32 v31, v32, v33
	global_store_dwordx2 v[26:27], v[30:31], off offset:1024
	v_lshl_add_u64 v[26:27], v[26:27], 0, s[12:13]
	s_waitcnt vmcnt(7)
	v_lshlrev_b32_e32 v100, 16, v72
	v_and_b32_e32 v101, 0xffff0000, v72
	v_lshlrev_b32_e32 v102, 16, v78
	v_and_b32_e32 v103, 0xffff0000, v78
	v_lshlrev_b32_e32 v104, 16, v73
	v_and_b32_e32 v105, 0xffff0000, v73
	v_lshlrev_b32_e32 v106, 16, v79
	v_and_b32_e32 v107, 0xffff0000, v79
	v_pk_mul_f32 v[30:31], v[100:101], v[102:103]
	v_pk_mul_f32 v[32:33], v[104:105], v[106:107]
	v_lshlrev_b32_e32 v100, 16, v74
	v_and_b32_e32 v101, 0xffff0000, v74
	v_lshlrev_b32_e32 v102, 16, v80
	v_and_b32_e32 v103, 0xffff0000, v80
	v_lshlrev_b32_e32 v104, 16, v75
	v_and_b32_e32 v105, 0xffff0000, v75
	v_lshlrev_b32_e32 v106, 16, v81
	v_and_b32_e32 v107, 0xffff0000, v81
	v_pk_mul_f32 v[34:35], v[100:101], v[102:103]
	v_pk_mul_f32 v[36:37], v[104:105], v[106:107]
	v_lshlrev_b32_e32 v100, 16, v76
	v_and_b32_e32 v101, 0xffff0000, v76
	v_lshlrev_b32_e32 v102, 16, v82
	v_and_b32_e32 v103, 0xffff0000, v82
	v_lshlrev_b32_e32 v104, 16, v77
	v_and_b32_e32 v105, 0xffff0000, v77
	v_lshlrev_b32_e32 v106, 16, v83
	v_and_b32_e32 v107, 0xffff0000, v83
	v_pk_mul_f32 v[108:109], v[100:101], v[102:103]
	v_pk_mul_f32 v[110:111], v[104:105], v[106:107]
	v_pk_mul_f32 v[32:33], v[10:11], v[32:33]
	v_pk_mul_f32 v[30:31], v[8:9], v[30:31]
	v_pk_fma_f32 v[32:33], v[6:7], v[36:37], v[32:33]
	v_pk_fma_f32 v[30:31], v[4:5], v[34:35], v[30:31]
	v_pk_fma_f32 v[30:31], v[0:1], v[108:109], v[30:31]
	v_pk_fma_f32 v[32:33], v[2:3], v[110:111], v[32:33]
	v_lshlrev_b32_e32 v100, 16, v84
	v_and_b32_e32 v101, 0xffff0000, v84
	v_lshlrev_b32_e32 v102, 16, v85
	v_and_b32_e32 v103, 0xffff0000, v85
	v_pk_mul_f32 v[32:33], v[32:33], v[102:103]
	v_pk_mul_f32 v[30:31], v[30:31], v[100:101]
	v_cvt_pk_bf16_f32 v30, v30, v31
	v_cvt_pk_bf16_f32 v31, v32, v33
	global_store_dwordx2 v[26:27], v[30:31], off offset:1024
	v_lshl_add_u64 v[26:27], v[26:27], 0, s[12:13]
	s_waitcnt vmcnt(0)
	v_lshlrev_b32_e32 v100, 16, v86
	v_and_b32_e32 v101, 0xffff0000, v86
	v_lshlrev_b32_e32 v102, 16, v92
	v_and_b32_e32 v103, 0xffff0000, v92
	v_lshlrev_b32_e32 v104, 16, v87
	v_and_b32_e32 v105, 0xffff0000, v87
	v_lshlrev_b32_e32 v106, 16, v93
	v_and_b32_e32 v107, 0xffff0000, v93
	v_pk_mul_f32 v[30:31], v[100:101], v[102:103]
	v_pk_mul_f32 v[32:33], v[104:105], v[106:107]
	v_lshlrev_b32_e32 v100, 16, v88
	v_and_b32_e32 v101, 0xffff0000, v88
	v_lshlrev_b32_e32 v102, 16, v94
	v_and_b32_e32 v103, 0xffff0000, v94
	v_lshlrev_b32_e32 v104, 16, v89
	v_and_b32_e32 v105, 0xffff0000, v89
	v_lshlrev_b32_e32 v106, 16, v95
	v_and_b32_e32 v107, 0xffff0000, v95
	v_pk_mul_f32 v[34:35], v[100:101], v[102:103]
	v_pk_mul_f32 v[36:37], v[104:105], v[106:107]
	v_lshlrev_b32_e32 v100, 16, v90
	v_and_b32_e32 v101, 0xffff0000, v90
	v_lshlrev_b32_e32 v102, 16, v96
	v_and_b32_e32 v103, 0xffff0000, v96
	v_lshlrev_b32_e32 v104, 16, v91
	v_and_b32_e32 v105, 0xffff0000, v91
	v_lshlrev_b32_e32 v106, 16, v97
	v_and_b32_e32 v107, 0xffff0000, v97
	v_pk_mul_f32 v[108:109], v[100:101], v[102:103]
	v_pk_mul_f32 v[110:111], v[104:105], v[106:107]
	v_cmp_gt_i32_e32 vcc, s36, v28
	s_nop 1
	v_cndmask_b32_e32 v108, 0, v108, vcc
	v_cndmask_b32_e32 v109, 0, v109, vcc
	v_cndmask_b32_e32 v110, 0, v110, vcc
	v_cndmask_b32_e32 v111, 0, v111, vcc
	v_pk_mul_f32 v[32:33], v[10:11], v[32:33]
	v_pk_mul_f32 v[30:31], v[8:9], v[30:31]
	v_pk_fma_f32 v[32:33], v[6:7], v[36:37], v[32:33]
	v_pk_fma_f32 v[30:31], v[4:5], v[34:35], v[30:31]
	v_pk_fma_f32 v[30:31], v[0:1], v[108:109], v[30:31]
	v_pk_fma_f32 v[32:33], v[2:3], v[110:111], v[32:33]
	v_lshlrev_b32_e32 v100, 16, v98
	v_and_b32_e32 v101, 0xffff0000, v98
	v_lshlrev_b32_e32 v102, 16, v99
	v_and_b32_e32 v103, 0xffff0000, v99
	v_pk_mul_f32 v[32:33], v[32:33], v[102:103]
	v_pk_mul_f32 v[30:31], v[30:31], v[100:101]
	v_cvt_pk_bf16_f32 v30, v30, v31
	v_cvt_pk_bf16_f32 v31, v32, v33
	global_store_dwordx2 v[26:27], v[30:31], off offset:1024
	s_add_u32 s12, s4, 0xfea4400
	s_addc_u32 s13, s5, 0
	v_ashrrev_i32_e32 v42, 6, v40
	v_cmp_lt_i32_e32 vcc, 3, v42
	s_nop 0
	v_readfirstlane_b32 s22, v42
	s_cmp_gt_i32 s22, 3
	s_cbranch_scc1 .Lprio_young
	s_setprio 0
	s_branch .Lprio_done
.Lprio_young:
	s_setprio 1
.Lprio_done:
	v_and_b32_e32 v41, 15, v40
	v_lshl_or_b32 v0, v42, 4, v41
	s_add_i32 s24, s24, s25
	v_add_u32_e32 v104, s24, v0
	v_ashrrev_i32_e32 v105, 31, v104
	v_lshlrev_b64 v[0:1], 10, v[104:105]
	v_lshl_add_u64 v[0:1], s[4:5], 0, v[0:1]
	s_lshl_b32 s58, s35, 8
	v_lshl_add_u64 v[0:1], v[0:1], 0, s[58:59]
	v_and_b32_e32 v132, 48, v40
	v_lshl_add_u64 v[0:1], v[0:1], 0, v[132:133]
	s_mov_b64 s[4:5], 0xa2a4400
	v_lshl_add_u64 v[8:9], v[0:1], 0, s[4:5]
	s_mov_b32 s4, 0xa2a4000
	v_add_co_u32_e32 v10, vcc, s4, v0
	v_ashrrev_i32_e32 v36, 3, v40
	s_nop 0
	v_addc_co_u32_e32 v11, vcc, 0, v1, vcc
	global_load_dwordx4 v[0:3], v[8:9], off offset:64
	global_load_dwordx4 v[4:7], v[8:9], off offset:128
	global_load_dwordx4 v[12:15], v[10:11], off offset:1024
	s_nop 0
	global_load_dwordx4 v[8:11], v[8:9], off offset:192
	v_ashrrev_i32_e32 v37, 31, v36
	v_lshlrev_b64 v[34:35], 8, v[36:37]
	v_and_b32_e32 v37, 7, v40
	v_lshl_or_b32 v16, v37, 5, v34
	v_mov_b32_e32 v17, v35
	v_lshl_add_u64 v[32:33], s[18:19], 0, v[16:17]
	s_mov_b64 s[24:25], 0xc010
	v_and_b32_e32 v43, 63, v40
	v_bfe_u32 v105, v40, 4, 2
	s_lshl_b32 s22, s35, 7
	s_mov_b32 s4, 0
	s_lshr_b32 s23, s34, 6
	v_lshl_add_u64 v[38:39], v[32:33], 0, s[24:25]
	v_mov_b32_e32 v44, 0
